# nt hint on the merge epilogue's once-read gate loads and on the layer-0 HX loop's input-row loads (on top of the nt ninth-round conversion stream)
# baseline (speedup 1.0000x reference)
.LBB0_218:
	s_add_i32 s100, s40, s42
	s_cmpk_lt_i32 s100, 0x4400
	s_cbranch_scc0 .Lhx_single
	s_add_i32 s7, s40, 0xffffc000
	s_cmpk_lt_i32 s40, 0x4000
	s_cselect_b32 s9, s41, 0
	s_cselect_b32 s8, s40, s7
	s_cselect_b32 s7, s37, s39
	s_cselect_b32 s10, s36, s38
	s_lshl_b64 s[8:9], s[8:9], 12
	s_add_u32 s8, s10, s8
	s_addc_u32 s9, s7, s9
	global_load_dwordx4 v[16:19], v[4:5], off nt
	global_load_dwordx4 v[20:23], v[4:5], off offset:1024 nt
	global_load_dwordx4 v[24:27], v[4:5], off offset:2048 nt
	global_load_dwordx4 v[28:31], v[4:5], off offset:3072 nt
	global_load_dwordx4 v[32:35], v11, s[8:9]
	global_load_dwordx4 v[36:39], v11, s[8:9] offset:1024
	global_load_dwordx4 v[40:43], v11, s[8:9] offset:2048
	global_load_dwordx4 v[44:47], v11, s[8:9] offset:3072
	s_min_i32 s7, s40, 0x4000
	s_ashr_i32 s7, s7, 12
	s_mul_hi_i32 s9, s7, 0x3000
	s_mulk_i32 s7, 0x3000
	s_add_u32 s8, s4, s7
	s_addc_u32 s9, s5, s9
	s_add_u32 s10, s8, 0x1000
	s_addc_u32 s11, s9, 0
	global_load_dwordx4 v[48:51], v11, s[8:9]
	global_load_dwordx4 v[52:55], v11, s[8:9] offset:1024
	global_load_dwordx4 v[56:59], v11, s[8:9] offset:2048
	global_load_dwordx4 v[60:63], v11, s[8:9] offset:3072
	global_load_dwordx4 v[64:67], v11, s[10:11]
	global_load_dwordx4 v[68:71], v13, s[10:11]
	global_load_dwordx4 v[72:75], v14, s[10:11]
	global_load_dwordx4 v[76:79], v15, s[10:11]
	s_add_u32 s40, s40, s42
	s_addc_u32 s41, s41, s43
	s_add_i32 s7, s40, 0xffffc000
	s_cmpk_lt_i32 s40, 0x4000
	s_cselect_b32 s9, s41, 0
	s_cselect_b32 s8, s40, s7
	s_cselect_b32 s7, s37, s39
	s_cselect_b32 s10, s36, s38
	s_lshl_b64 s[8:9], s[8:9], 12
	s_add_u32 s8, s10, s8
	s_addc_u32 s9, s7, s9
	global_load_dwordx4 v[124:127], v[4:5], off nt
	global_load_dwordx4 v[128:131], v[4:5], off offset:1024 nt
	global_load_dwordx4 v[132:135], v[4:5], off offset:2048 nt
	global_load_dwordx4 v[136:139], v[4:5], off offset:3072 nt
	global_load_dwordx4 v[140:143], v11, s[8:9]
	global_load_dwordx4 v[144:147], v11, s[8:9] offset:1024
	global_load_dwordx4 v[148:151], v11, s[8:9] offset:2048
	global_load_dwordx4 v[152:155], v11, s[8:9] offset:3072
	s_min_i32 s7, s40, 0x4000
	s_ashr_i32 s7, s7, 12
	s_mul_hi_i32 s9, s7, 0x3000
	s_mulk_i32 s7, 0x3000
	s_add_u32 s8, s4, s7
	s_addc_u32 s9, s5, s9
	s_add_u32 s10, s8, 0x1000
	s_addc_u32 s11, s9, 0
	global_load_dwordx4 v[156:159], v11, s[8:9]
	global_load_dwordx4 v[160:163], v11, s[8:9] offset:1024
	global_load_dwordx4 v[164:167], v11, s[8:9] offset:2048
	global_load_dwordx4 v[168:171], v11, s[8:9] offset:3072
	global_load_dwordx4 v[172:175], v11, s[10:11]
	global_load_dwordx4 v[176:179], v13, s[10:11]
	global_load_dwordx4 v[180:183], v14, s[10:11]
	global_load_dwordx4 v[184:187], v15, s[10:11]
	s_add_u32 s40, s40, s42
	s_addc_u32 s41, s41, s43
	s_waitcnt vmcnt(27)
	v_pk_mul_f32 v[80:81], v[34:35], v[34:35]
	v_pk_mul_f32 v[82:83], v[32:33], v[32:33]
	s_waitcnt vmcnt(26)
	v_pk_mul_f32 v[84:85], v[38:39], v[38:39]
	v_pk_mul_f32 v[86:87], v[36:37], v[36:37]
	v_pk_mov_b32 v[92:93], v[82:83], v[80:81] op_sel:[1,0]
	v_mov_b32_e32 v83, v81
	v_pk_mov_b32 v[80:81], v[86:87], v[84:85] op_sel:[1,0]
	v_mov_b32_e32 v87, v85
	s_waitcnt vmcnt(25)
	v_mul_f32_e32 v88, v40, v40
	v_mul_f32_e32 v90, v42, v42
	v_pk_add_f32 v[82:83], v[92:93], v[82:83]
	v_pk_add_f32 v[80:81], v[80:81], v[86:87]
	v_pk_fma_f32 v[84:85], v[40:41], v[40:41], v[88:89] op_sel_hi:[1,1,0]
	v_pk_fma_f32 v[88:89], v[42:43], v[42:43], v[90:91] op_sel_hi:[1,1,0]
	v_pk_add_f32 v[82:83], v[82:83], v[82:83] op_sel_hi:[0,1]
	v_pk_add_f32 v[80:81], v[80:81], v[80:81] op_sel_hi:[0,1]
	s_waitcnt vmcnt(24)
	v_mul_f32_e32 v84, v44, v44
	v_mul_f32_e32 v88, v45, v45
	v_mul_f32_e32 v82, v46, v46
	v_mul_f32_e32 v80, v47, v47
	v_pk_add_f32 v[84:85], v[84:85], v[88:89]
	v_pk_add_f32 v[80:81], v[82:83], v[80:81]
	s_waitcnt vmcnt(19)
	v_pk_add_f32 v[66:67], v[66:67], 1.0 op_sel_hi:[1,0]
	v_pk_add_f32 v[80:81], v[84:85], v[80:81]
	v_pk_add_f32 v[64:65], v[64:65], 1.0 op_sel_hi:[1,0]
	v_add_f32_e32 v80, v80, v81
	ds_bpermute_b32 v81, v1, v80
	s_waitcnt vmcnt(18)
	v_pk_add_f32 v[70:71], v[70:71], 1.0 op_sel_hi:[1,0]
	v_pk_add_f32 v[68:69], v[68:69], 1.0 op_sel_hi:[1,0]
	s_waitcnt vmcnt(17)
	v_pk_add_f32 v[74:75], v[74:75], 1.0 op_sel_hi:[1,0]
	v_pk_add_f32 v[72:73], v[72:73], 1.0 op_sel_hi:[1,0]
	s_waitcnt lgkmcnt(0)
	v_add_f32_e32 v80, v80, v81
	ds_bpermute_b32 v81, v6, v80
	s_waitcnt vmcnt(16)
	v_pk_add_f32 v[78:79], v[78:79], 1.0 op_sel_hi:[1,0]
	v_pk_add_f32 v[76:77], v[76:77], 1.0 op_sel_hi:[1,0]
	s_waitcnt lgkmcnt(0)
	v_add_f32_e32 v80, v80, v81
	ds_bpermute_b32 v81, v7, v80
	s_waitcnt lgkmcnt(0)
	v_add_f32_e32 v80, v80, v81
	ds_bpermute_b32 v81, v8, v80
	s_waitcnt lgkmcnt(0)
	v_add_f32_e32 v80, v80, v81
	ds_bpermute_b32 v81, v9, v80
	s_waitcnt lgkmcnt(0)
	v_add_f32_e32 v80, v80, v81
	ds_bpermute_b32 v81, v10, v80
	s_waitcnt lgkmcnt(0)
	v_add_f32_e32 v80, v80, v81
	v_fmamk_f32 v80, v80, 0x3a800000, v12
	v_mul_f32_e32 v81, 0x4b800000, v80
	v_cmp_gt_f32_e32 vcc, s6, v80
	s_nop 1
	v_cndmask_b32_e32 v80, v80, v81, vcc
	v_rsq_f32_e32 v80, v80
	s_nop 0
	v_mul_f32_e32 v81, 0x45800000, v80
	v_cndmask_b32_e32 v80, v80, v81, vcc
	v_pk_mul_f32 v[34:35], v[34:35], v[80:81] op_sel_hi:[1,0]
	v_pk_mul_f32 v[32:33], v[32:33], v[80:81] op_sel_hi:[1,0]
	v_pk_mul_f32 v[38:39], v[38:39], v[80:81] op_sel_hi:[1,0]
	v_pk_mul_f32 v[36:37], v[36:37], v[80:81] op_sel_hi:[1,0]
	v_pk_mul_f32 v[42:43], v[42:43], v[80:81] op_sel_hi:[1,0]
	v_pk_mul_f32 v[40:41], v[40:41], v[80:81] op_sel_hi:[1,0]
	v_pk_mul_f32 v[46:47], v[46:47], v[80:81] op_sel_hi:[1,0]
	v_pk_mul_f32 v[44:45], v[44:45], v[80:81] op_sel_hi:[1,0]
	v_pk_mul_f32 v[16:17], v[16:17], v[32:33]
	v_pk_mul_f32 v[18:19], v[18:19], v[34:35]
	v_pk_mul_f32 v[20:21], v[20:21], v[36:37]
	v_pk_mul_f32 v[22:23], v[22:23], v[38:39]
	v_pk_mul_f32 v[24:25], v[24:25], v[40:41]
	v_pk_mul_f32 v[26:27], v[26:27], v[42:43]
	v_pk_mul_f32 v[28:29], v[28:29], v[44:45]
	v_pk_mul_f32 v[30:31], v[30:31], v[46:47]
	v_pk_fma_f32 v[18:19], v[66:67], v[18:19], v[50:51]
	v_pk_fma_f32 v[16:17], v[64:65], v[16:17], v[48:49]
	v_pk_fma_f32 v[22:23], v[70:71], v[22:23], v[54:55]
	v_pk_fma_f32 v[20:21], v[68:69], v[20:21], v[52:53]
	v_pk_fma_f32 v[26:27], v[74:75], v[26:27], v[58:59]
	v_pk_fma_f32 v[24:25], v[72:73], v[24:25], v[56:57]
	v_pk_fma_f32 v[30:31], v[78:79], v[30:31], v[62:63]
	v_pk_fma_f32 v[28:29], v[76:77], v[28:29], v[60:61]
	v_cvt_pk_bf16_f32 v16, v16, v17
	v_cvt_pk_bf16_f32 v17, v18, v19
	v_cvt_pk_bf16_f32 v18, v20, v21
	v_cvt_pk_bf16_f32 v19, v22, v23
	v_cvt_pk_bf16_f32 v20, v24, v25
	v_cvt_pk_bf16_f32 v21, v26, v27
	v_cvt_pk_bf16_f32 v22, v28, v29
	v_cvt_pk_bf16_f32 v23, v30, v31
	global_store_dwordx2 v[2:3], v[16:17], off
	global_store_dwordx2 v[2:3], v[18:19], off offset:512
	global_store_dwordx2 v[2:3], v[20:21], off offset:1024
	global_store_dwordx2 v[2:3], v[22:23], off offset:1536
	v_lshl_add_u64 v[2:3], v[2:3], 0, s[0:1]
	s_waitcnt vmcnt(15)
	v_pk_mul_f32 v[188:189], v[142:143], v[142:143]
	v_pk_mul_f32 v[190:191], v[140:141], v[140:141]
	s_waitcnt vmcnt(14)
	v_pk_mul_f32 v[192:193], v[146:147], v[146:147]
	v_pk_mul_f32 v[194:195], v[144:145], v[144:145]
	v_pk_mov_b32 v[200:201], v[190:191], v[188:189] op_sel:[1,0]
	v_mov_b32_e32 v191, v189
	v_pk_mov_b32 v[188:189], v[194:195], v[192:193] op_sel:[1,0]
	v_mov_b32_e32 v195, v193
	s_waitcnt vmcnt(13)
	v_mul_f32_e32 v196, v148, v148
	v_mul_f32_e32 v198, v150, v150
	v_pk_add_f32 v[190:191], v[200:201], v[190:191]
	v_pk_add_f32 v[188:189], v[188:189], v[194:195]
	v_pk_fma_f32 v[192:193], v[148:149], v[148:149], v[196:197] op_sel_hi:[1,1,0]
	v_pk_fma_f32 v[196:197], v[150:151], v[150:151], v[198:199] op_sel_hi:[1,1,0]
	v_pk_add_f32 v[190:191], v[190:191], v[190:191] op_sel_hi:[0,1]
	v_pk_add_f32 v[188:189], v[188:189], v[188:189] op_sel_hi:[0,1]
	s_waitcnt vmcnt(12)
	v_mul_f32_e32 v192, v152, v152
	v_mul_f32_e32 v196, v153, v153
	v_mul_f32_e32 v190, v154, v154
	v_mul_f32_e32 v188, v155, v155
	v_pk_add_f32 v[192:193], v[192:193], v[196:197]
	v_pk_add_f32 v[188:189], v[190:191], v[188:189]
	s_waitcnt vmcnt(7)
	v_pk_add_f32 v[174:175], v[174:175], 1.0 op_sel_hi:[1,0]
	v_pk_add_f32 v[188:189], v[192:193], v[188:189]
	v_pk_add_f32 v[172:173], v[172:173], 1.0 op_sel_hi:[1,0]
	v_add_f32_e32 v188, v188, v189
	ds_bpermute_b32 v189, v1, v188
	s_waitcnt vmcnt(6)
	v_pk_add_f32 v[178:179], v[178:179], 1.0 op_sel_hi:[1,0]
	v_pk_add_f32 v[176:177], v[176:177], 1.0 op_sel_hi:[1,0]
	s_waitcnt vmcnt(5)
	v_pk_add_f32 v[182:183], v[182:183], 1.0 op_sel_hi:[1,0]
	v_pk_add_f32 v[180:181], v[180:181], 1.0 op_sel_hi:[1,0]
	s_waitcnt lgkmcnt(0)
	v_add_f32_e32 v188, v188, v189
	ds_bpermute_b32 v189, v6, v188
	s_waitcnt vmcnt(4)
	v_pk_add_f32 v[186:187], v[186:187], 1.0 op_sel_hi:[1,0]
	v_pk_add_f32 v[184:185], v[184:185], 1.0 op_sel_hi:[1,0]
	s_waitcnt lgkmcnt(0)
	v_add_f32_e32 v188, v188, v189
	ds_bpermute_b32 v189, v7, v188
	s_waitcnt lgkmcnt(0)
	v_add_f32_e32 v188, v188, v189
	ds_bpermute_b32 v189, v8, v188
	s_waitcnt lgkmcnt(0)
	v_add_f32_e32 v188, v188, v189
	ds_bpermute_b32 v189, v9, v188
	s_waitcnt lgkmcnt(0)
	v_add_f32_e32 v188, v188, v189
	ds_bpermute_b32 v189, v10, v188
	s_waitcnt lgkmcnt(0)
	v_add_f32_e32 v188, v188, v189
	v_fmamk_f32 v188, v188, 0x3a800000, v12
	v_mul_f32_e32 v189, 0x4b800000, v188
	v_cmp_gt_f32_e32 vcc, s6, v188
	s_nop 1
	v_cndmask_b32_e32 v188, v188, v189, vcc
	v_rsq_f32_e32 v188, v188
	s_nop 0
	v_mul_f32_e32 v189, 0x45800000, v188
	v_cndmask_b32_e32 v188, v188, v189, vcc
	v_pk_mul_f32 v[142:143], v[142:143], v[188:189] op_sel_hi:[1,0]
	v_pk_mul_f32 v[140:141], v[140:141], v[188:189] op_sel_hi:[1,0]
	v_pk_mul_f32 v[146:147], v[146:147], v[188:189] op_sel_hi:[1,0]
	v_pk_mul_f32 v[144:145], v[144:145], v[188:189] op_sel_hi:[1,0]
	v_pk_mul_f32 v[150:151], v[150:151], v[188:189] op_sel_hi:[1,0]
	v_pk_mul_f32 v[148:149], v[148:149], v[188:189] op_sel_hi:[1,0]
	v_pk_mul_f32 v[154:155], v[154:155], v[188:189] op_sel_hi:[1,0]
	v_pk_mul_f32 v[152:153], v[152:153], v[188:189] op_sel_hi:[1,0]
	v_pk_mul_f32 v[124:125], v[124:125], v[140:141]
	v_pk_mul_f32 v[126:127], v[126:127], v[142:143]
	v_pk_mul_f32 v[128:129], v[128:129], v[144:145]
	v_pk_mul_f32 v[130:131], v[130:131], v[146:147]
	v_pk_mul_f32 v[132:133], v[132:133], v[148:149]
	v_pk_mul_f32 v[134:135], v[134:135], v[150:151]
	v_pk_mul_f32 v[136:137], v[136:137], v[152:153]
	v_pk_mul_f32 v[138:139], v[138:139], v[154:155]
	v_pk_fma_f32 v[126:127], v[174:175], v[126:127], v[158:159]
	v_pk_fma_f32 v[124:125], v[172:173], v[124:125], v[156:157]
	v_pk_fma_f32 v[130:131], v[178:179], v[130:131], v[162:163]
	v_pk_fma_f32 v[128:129], v[176:177], v[128:129], v[160:161]
	v_pk_fma_f32 v[134:135], v[182:183], v[134:135], v[166:167]
	v_pk_fma_f32 v[132:133], v[180:181], v[132:133], v[164:165]
	v_pk_fma_f32 v[138:139], v[186:187], v[138:139], v[170:171]
	v_pk_fma_f32 v[136:137], v[184:185], v[136:137], v[168:169]
	v_cvt_pk_bf16_f32 v124, v124, v125
	v_cvt_pk_bf16_f32 v125, v126, v127
	v_cvt_pk_bf16_f32 v126, v128, v129
	v_cvt_pk_bf16_f32 v127, v130, v131
	v_cvt_pk_bf16_f32 v128, v132, v133
	v_cvt_pk_bf16_f32 v129, v134, v135
	v_cvt_pk_bf16_f32 v130, v136, v137
	v_cvt_pk_bf16_f32 v131, v138, v139
	global_store_dwordx2 v[2:3], v[124:125], off
	global_store_dwordx2 v[2:3], v[126:127], off offset:512
	global_store_dwordx2 v[2:3], v[128:129], off offset:1024
	global_store_dwordx2 v[2:3], v[130:131], off offset:1536
	v_lshl_add_u64 v[2:3], v[2:3], 0, s[0:1]
	s_cmpk_lt_i32 s40, 0x4400
	s_cbranch_scc1 .LBB0_218
	s_branch .Lhx_done
.Lhx_single:
	s_add_i32 s7, s40, 0xffffc000
	s_cmpk_lt_i32 s40, 0x4000
	s_cselect_b32 s9, s41, 0
	s_cselect_b32 s8, s40, s7
	s_cselect_b32 s7, s37, s39
	s_cselect_b32 s10, s36, s38
	s_lshl_b64 s[8:9], s[8:9], 12
	s_add_u32 s8, s10, s8
	s_addc_u32 s9, s7, s9
	global_load_dwordx4 v[16:19], v[4:5], off nt
	global_load_dwordx4 v[20:23], v[4:5], off offset:1024 nt
	global_load_dwordx4 v[24:27], v[4:5], off offset:2048 nt
	global_load_dwordx4 v[28:31], v[4:5], off offset:3072 nt
	global_load_dwordx4 v[32:35], v11, s[8:9]
	global_load_dwordx4 v[36:39], v11, s[8:9] offset:1024
	global_load_dwordx4 v[40:43], v11, s[8:9] offset:2048
	global_load_dwordx4 v[44:47], v11, s[8:9] offset:3072
	s_min_i32 s7, s40, 0x4000
	s_ashr_i32 s7, s7, 12
	s_mul_hi_i32 s9, s7, 0x3000
	s_mulk_i32 s7, 0x3000
	s_add_u32 s8, s4, s7
	s_addc_u32 s9, s5, s9
	s_add_u32 s10, s8, 0x1000
	s_addc_u32 s11, s9, 0
	global_load_dwordx4 v[48:51], v11, s[8:9]
	global_load_dwordx4 v[52:55], v11, s[8:9] offset:1024
	global_load_dwordx4 v[56:59], v11, s[8:9] offset:2048
	global_load_dwordx4 v[60:63], v11, s[8:9] offset:3072
	global_load_dwordx4 v[64:67], v11, s[10:11]
	global_load_dwordx4 v[68:71], v13, s[10:11]
	global_load_dwordx4 v[72:75], v14, s[10:11]
	global_load_dwordx4 v[76:79], v15, s[10:11]
	s_add_u32 s40, s40, s42
	s_addc_u32 s41, s41, s43
	s_waitcnt vmcnt(11)
	v_pk_mul_f32 v[80:81], v[34:35], v[34:35]
	v_pk_mul_f32 v[82:83], v[32:33], v[32:33]
	s_waitcnt vmcnt(10)
	v_pk_mul_f32 v[84:85], v[38:39], v[38:39]
	v_pk_mul_f32 v[86:87], v[36:37], v[36:37]
	v_pk_mov_b32 v[92:93], v[82:83], v[80:81] op_sel:[1,0]
	v_mov_b32_e32 v83, v81
	v_pk_mov_b32 v[80:81], v[86:87], v[84:85] op_sel:[1,0]
	v_mov_b32_e32 v87, v85
	s_waitcnt vmcnt(9)
	v_mul_f32_e32 v88, v40, v40
	v_mul_f32_e32 v90, v42, v42
	v_pk_add_f32 v[82:83], v[92:93], v[82:83]
	v_pk_add_f32 v[80:81], v[80:81], v[86:87]
	v_pk_fma_f32 v[84:85], v[40:41], v[40:41], v[88:89] op_sel_hi:[1,1,0]
	v_pk_fma_f32 v[88:89], v[42:43], v[42:43], v[90:91] op_sel_hi:[1,1,0]
	v_pk_add_f32 v[82:83], v[82:83], v[82:83] op_sel_hi:[0,1]
	v_pk_add_f32 v[80:81], v[80:81], v[80:81] op_sel_hi:[0,1]
	s_waitcnt vmcnt(8)
	v_mul_f32_e32 v84, v44, v44
	v_mul_f32_e32 v88, v45, v45
	v_mul_f32_e32 v82, v46, v46
	v_mul_f32_e32 v80, v47, v47
	v_pk_add_f32 v[84:85], v[84:85], v[88:89]
	v_pk_add_f32 v[80:81], v[82:83], v[80:81]
	s_waitcnt vmcnt(3)
	v_pk_add_f32 v[66:67], v[66:67], 1.0 op_sel_hi:[1,0]
	v_pk_add_f32 v[80:81], v[84:85], v[80:81]
	v_pk_add_f32 v[64:65], v[64:65], 1.0 op_sel_hi:[1,0]
	v_add_f32_e32 v80, v80, v81
	ds_bpermute_b32 v81, v1, v80
	s_waitcnt vmcnt(2)
	v_pk_add_f32 v[70:71], v[70:71], 1.0 op_sel_hi:[1,0]
	v_pk_add_f32 v[68:69], v[68:69], 1.0 op_sel_hi:[1,0]
	s_waitcnt vmcnt(1)
	v_pk_add_f32 v[74:75], v[74:75], 1.0 op_sel_hi:[1,0]
	v_pk_add_f32 v[72:73], v[72:73], 1.0 op_sel_hi:[1,0]
	s_waitcnt lgkmcnt(0)
	v_add_f32_e32 v80, v80, v81
	ds_bpermute_b32 v81, v6, v80
	s_waitcnt vmcnt(0)
	v_pk_add_f32 v[78:79], v[78:79], 1.0 op_sel_hi:[1,0]
	v_pk_add_f32 v[76:77], v[76:77], 1.0 op_sel_hi:[1,0]
	s_waitcnt lgkmcnt(0)
	v_add_f32_e32 v80, v80, v81
	ds_bpermute_b32 v81, v7, v80
	s_waitcnt lgkmcnt(0)
	v_add_f32_e32 v80, v80, v81
	ds_bpermute_b32 v81, v8, v80
	s_waitcnt lgkmcnt(0)
	v_add_f32_e32 v80, v80, v81
	ds_bpermute_b32 v81, v9, v80
	s_waitcnt lgkmcnt(0)
	v_add_f32_e32 v80, v80, v81
	ds_bpermute_b32 v81, v10, v80
	s_waitcnt lgkmcnt(0)
	v_add_f32_e32 v80, v80, v81
	v_fmamk_f32 v80, v80, 0x3a800000, v12
	v_mul_f32_e32 v81, 0x4b800000, v80
	v_cmp_gt_f32_e32 vcc, s6, v80
	s_nop 1
	v_cndmask_b32_e32 v80, v80, v81, vcc
	v_rsq_f32_e32 v80, v80
	s_nop 0
	v_mul_f32_e32 v81, 0x45800000, v80
	v_cndmask_b32_e32 v80, v80, v81, vcc
	v_pk_mul_f32 v[34:35], v[34:35], v[80:81] op_sel_hi:[1,0]
	v_pk_mul_f32 v[32:33], v[32:33], v[80:81] op_sel_hi:[1,0]
	v_pk_mul_f32 v[38:39], v[38:39], v[80:81] op_sel_hi:[1,0]
	v_pk_mul_f32 v[36:37], v[36:37], v[80:81] op_sel_hi:[1,0]
	v_pk_mul_f32 v[42:43], v[42:43], v[80:81] op_sel_hi:[1,0]
	v_pk_mul_f32 v[40:41], v[40:41], v[80:81] op_sel_hi:[1,0]
	v_pk_mul_f32 v[46:47], v[46:47], v[80:81] op_sel_hi:[1,0]
	v_pk_mul_f32 v[44:45], v[44:45], v[80:81] op_sel_hi:[1,0]
	v_pk_mul_f32 v[16:17], v[16:17], v[32:33]
	v_pk_mul_f32 v[18:19], v[18:19], v[34:35]
	v_pk_mul_f32 v[20:21], v[20:21], v[36:37]
	v_pk_mul_f32 v[22:23], v[22:23], v[38:39]
	v_pk_mul_f32 v[24:25], v[24:25], v[40:41]
	v_pk_mul_f32 v[26:27], v[26:27], v[42:43]
	v_pk_mul_f32 v[28:29], v[28:29], v[44:45]
	v_pk_mul_f32 v[30:31], v[30:31], v[46:47]
	v_pk_fma_f32 v[18:19], v[66:67], v[18:19], v[50:51]
	v_pk_fma_f32 v[16:17], v[64:65], v[16:17], v[48:49]
	v_pk_fma_f32 v[22:23], v[70:71], v[22:23], v[54:55]
	v_pk_fma_f32 v[20:21], v[68:69], v[20:21], v[52:53]
	v_pk_fma_f32 v[26:27], v[74:75], v[26:27], v[58:59]
	v_pk_fma_f32 v[24:25], v[72:73], v[24:25], v[56:57]
	v_pk_fma_f32 v[30:31], v[78:79], v[30:31], v[62:63]
	v_pk_fma_f32 v[28:29], v[76:77], v[28:29], v[60:61]
	v_cvt_pk_bf16_f32 v16, v16, v17
	v_cvt_pk_bf16_f32 v17, v18, v19
	v_cvt_pk_bf16_f32 v18, v20, v21
	v_cvt_pk_bf16_f32 v19, v22, v23
	v_cvt_pk_bf16_f32 v20, v24, v25
	v_cvt_pk_bf16_f32 v21, v26, v27
	v_cvt_pk_bf16_f32 v22, v28, v29
	v_cvt_pk_bf16_f32 v23, v30, v31
	global_store_dwordx2 v[2:3], v[16:17], off
	global_store_dwordx2 v[2:3], v[18:19], off offset:512
	global_store_dwordx2 v[2:3], v[20:21], off offset:1024
	global_store_dwordx2 v[2:3], v[22:23], off offset:1536
	v_lshl_add_u64 v[2:3], v[2:3], 0, s[0:1]

.LBB0_902:
	s_lshl_b32 s0, s73, 2
	s_lshl_b32 s38, s72, 4
	s_add_i32 s0, s0, s71
	s_add_i32 s10, s0, s38
	s_ashr_i32 s11, s10, 31
	s_lshl_b64 s[10:11], s[10:11], 16
	v_lshl_add_u64 v[210:211], v[204:205], 0, s[10:11]
	s_mov_b64 s[10:11], 0x1000
	v_lshl_add_u64 v[212:213], v[210:211], 0, s[10:11]
	s_mov_b64 s[10:11], 0x10000
	v_lshl_add_u64 v[214:215], v[210:211], 0, s[10:11]
	s_mov_b64 s[10:11], 0x11000
	v_lshl_add_u64 v[218:219], v[210:211], 0, s[10:11]
	global_load_dwordx4 v[190:193], v[210:211], off nt
	global_load_dwordx4 v[182:185], v[210:211], off offset:1024 nt
	global_load_dwordx4 v[174:177], v[210:211], off offset:2048 nt
	global_load_dwordx4 v[166:169], v[210:211], off offset:3072 nt
	global_load_dwordx4 v[158:161], v[212:213], off nt
	global_load_dwordx4 v[150:153], v[212:213], off offset:1024 nt
	global_load_dwordx4 v[142:145], v[212:213], off offset:2048 nt
	global_load_dwordx4 v[134:137], v[212:213], off offset:3072 nt
	s_cmp_gt_i32 s71, 2
	s_cbranch_scc1 .Lwo_eq3
	global_load_dwordx4 v[194:197], v[214:215], off nt
	global_load_dwordx4 v[186:189], v[214:215], off offset:1024 nt
	global_load_dwordx4 v[178:181], v[214:215], off offset:2048 nt
	global_load_dwordx4 v[170:173], v[214:215], off offset:3072 nt
	global_load_dwordx4 v[162:165], v[218:219], off nt
	global_load_dwordx4 v[154:157], v[218:219], off offset:1024 nt
	global_load_dwordx4 v[146:149], v[218:219], off offset:2048 nt
	global_load_dwordx4 v[138:141], v[218:219], off offset:3072 nt
	s_waitcnt vmcnt(0)
	v_cvt_f32_ubyte0_e32 v210, v190
	v_cvt_f32_ubyte1_e32 v211, v190
	v_cvt_f32_ubyte2_e32 v212, v190
	v_cvt_f32_ubyte3_e32 v213, v190
	v_cvt_f32_ubyte0_e32 v214, v194
	v_cvt_f32_ubyte1_e32 v215, v194
	v_cvt_f32_ubyte2_e32 v218, v194
	v_cvt_f32_ubyte3_e32 v219, v194
	v_rcp_iflag_f32_e32 v214, v214
	v_rcp_iflag_f32_e32 v215, v215
	v_rcp_iflag_f32_e32 v218, v218
	v_rcp_iflag_f32_e32 v219, v219
	v_mul_f32_e32 v210, v214, v210
	v_mul_f32_e32 v211, v215, v211
	v_mul_f32_e32 v212, v218, v212
	v_mul_f32_e32 v213, v219, v213
	v_pk_mul_f32 v[130:131], v[130:131], v[210:211]
	v_pk_mul_f32 v[132:133], v[132:133], v[212:213]
	v_cvt_f32_ubyte0_e32 v210, v191
	v_cvt_f32_ubyte1_e32 v211, v191
	v_cvt_f32_ubyte2_e32 v212, v191
	v_cvt_f32_ubyte3_e32 v213, v191
	v_cvt_f32_ubyte0_e32 v214, v195
	v_cvt_f32_ubyte1_e32 v215, v195
	v_cvt_f32_ubyte2_e32 v218, v195
	v_cvt_f32_ubyte3_e32 v219, v195
	v_rcp_iflag_f32_e32 v214, v214
	v_rcp_iflag_f32_e32 v215, v215
	v_rcp_iflag_f32_e32 v218, v218
	v_rcp_iflag_f32_e32 v219, v219
	v_mul_f32_e32 v210, v214, v210
	v_mul_f32_e32 v211, v215, v211
	v_mul_f32_e32 v212, v218, v212
	v_mul_f32_e32 v213, v219, v213
	v_pk_mul_f32 v[126:127], v[126:127], v[210:211]
	v_pk_mul_f32 v[128:129], v[128:129], v[212:213]
	v_cvt_f32_ubyte0_e32 v210, v192
	v_cvt_f32_ubyte1_e32 v211, v192
	v_cvt_f32_ubyte2_e32 v212, v192
	v_cvt_f32_ubyte3_e32 v213, v192
	v_cvt_f32_ubyte0_e32 v214, v196
	v_cvt_f32_ubyte1_e32 v215, v196
	v_cvt_f32_ubyte2_e32 v218, v196
	v_cvt_f32_ubyte3_e32 v219, v196
	v_rcp_iflag_f32_e32 v214, v214
	v_rcp_iflag_f32_e32 v215, v215
	v_rcp_iflag_f32_e32 v218, v218
	v_rcp_iflag_f32_e32 v219, v219
	v_mul_f32_e32 v210, v214, v210
	v_mul_f32_e32 v211, v215, v211
	v_mul_f32_e32 v212, v218, v212
	v_mul_f32_e32 v213, v219, v213
	v_pk_mul_f32 v[98:99], v[98:99], v[210:211]
	v_pk_mul_f32 v[100:101], v[100:101], v[212:213]
	v_cvt_f32_ubyte0_e32 v210, v193
	v_cvt_f32_ubyte1_e32 v211, v193
	v_cvt_f32_ubyte2_e32 v212, v193
	v_cvt_f32_ubyte3_e32 v213, v193
	v_cvt_f32_ubyte0_e32 v214, v197
	v_cvt_f32_ubyte1_e32 v215, v197
	v_cvt_f32_ubyte2_e32 v218, v197
	v_cvt_f32_ubyte3_e32 v219, v197
	v_rcp_iflag_f32_e32 v214, v214
	v_rcp_iflag_f32_e32 v215, v215
	v_rcp_iflag_f32_e32 v218, v218
	v_rcp_iflag_f32_e32 v219, v219
	v_mul_f32_e32 v210, v214, v210
	v_mul_f32_e32 v211, v215, v211
	v_mul_f32_e32 v212, v218, v212
	v_mul_f32_e32 v213, v219, v213
	v_pk_mul_f32 v[94:95], v[94:95], v[210:211]
	v_pk_mul_f32 v[96:97], v[96:97], v[212:213]
	v_cvt_f32_ubyte0_e32 v210, v182
	v_cvt_f32_ubyte1_e32 v211, v182
	v_cvt_f32_ubyte2_e32 v212, v182
	v_cvt_f32_ubyte3_e32 v213, v182
	v_cvt_f32_ubyte0_e32 v214, v186
	v_cvt_f32_ubyte1_e32 v215, v186
	v_cvt_f32_ubyte2_e32 v218, v186
	v_cvt_f32_ubyte3_e32 v219, v186
	v_rcp_iflag_f32_e32 v214, v214
	v_rcp_iflag_f32_e32 v215, v215
	v_rcp_iflag_f32_e32 v218, v218
	v_rcp_iflag_f32_e32 v219, v219
	v_mul_f32_e32 v210, v214, v210
	v_mul_f32_e32 v211, v215, v211
	v_mul_f32_e32 v212, v218, v212
	v_mul_f32_e32 v213, v219, v213
	v_pk_mul_f32 v[122:123], v[122:123], v[210:211]
	v_pk_mul_f32 v[124:125], v[124:125], v[212:213]
	v_cvt_f32_ubyte0_e32 v210, v183
	v_cvt_f32_ubyte1_e32 v211, v183
	v_cvt_f32_ubyte2_e32 v212, v183
	v_cvt_f32_ubyte3_e32 v213, v183
	v_cvt_f32_ubyte0_e32 v214, v187
	v_cvt_f32_ubyte1_e32 v215, v187
	v_cvt_f32_ubyte2_e32 v218, v187
	v_cvt_f32_ubyte3_e32 v219, v187
	v_rcp_iflag_f32_e32 v214, v214
	v_rcp_iflag_f32_e32 v215, v215
	v_rcp_iflag_f32_e32 v218, v218
	v_rcp_iflag_f32_e32 v219, v219
	v_mul_f32_e32 v210, v214, v210
	v_mul_f32_e32 v211, v215, v211
	v_mul_f32_e32 v212, v218, v212
	v_mul_f32_e32 v213, v219, v213
	v_pk_mul_f32 v[118:119], v[118:119], v[210:211]
	v_pk_mul_f32 v[120:121], v[120:121], v[212:213]
	v_cvt_f32_ubyte0_e32 v210, v184
	v_cvt_f32_ubyte1_e32 v211, v184
	v_cvt_f32_ubyte2_e32 v212, v184
	v_cvt_f32_ubyte3_e32 v213, v184
	v_cvt_f32_ubyte0_e32 v214, v188
	v_cvt_f32_ubyte1_e32 v215, v188
	v_cvt_f32_ubyte2_e32 v218, v188
	v_cvt_f32_ubyte3_e32 v219, v188
	v_rcp_iflag_f32_e32 v214, v214
	v_rcp_iflag_f32_e32 v215, v215
	v_rcp_iflag_f32_e32 v218, v218
	v_rcp_iflag_f32_e32 v219, v219
	v_mul_f32_e32 v210, v214, v210
	v_mul_f32_e32 v211, v215, v211
	v_mul_f32_e32 v212, v218, v212
	v_mul_f32_e32 v213, v219, v213
	v_pk_mul_f32 v[90:91], v[90:91], v[210:211]
	v_pk_mul_f32 v[92:93], v[92:93], v[212:213]
	v_cvt_f32_ubyte0_e32 v210, v185
	v_cvt_f32_ubyte1_e32 v211, v185
	v_cvt_f32_ubyte2_e32 v212, v185
	v_cvt_f32_ubyte3_e32 v213, v185
	v_cvt_f32_ubyte0_e32 v214, v189
	v_cvt_f32_ubyte1_e32 v215, v189
	v_cvt_f32_ubyte2_e32 v218, v189
	v_cvt_f32_ubyte3_e32 v219, v189
	v_rcp_iflag_f32_e32 v214, v214
	v_rcp_iflag_f32_e32 v215, v215
	v_rcp_iflag_f32_e32 v218, v218
	v_rcp_iflag_f32_e32 v219, v219
	v_mul_f32_e32 v210, v214, v210
	v_mul_f32_e32 v211, v215, v211
	v_mul_f32_e32 v212, v218, v212
	v_mul_f32_e32 v213, v219, v213
	v_pk_mul_f32 v[86:87], v[86:87], v[210:211]
	v_pk_mul_f32 v[88:89], v[88:89], v[212:213]
	v_cvt_f32_ubyte0_e32 v210, v174
	v_cvt_f32_ubyte1_e32 v211, v174
	v_cvt_f32_ubyte2_e32 v212, v174
	v_cvt_f32_ubyte3_e32 v213, v174
	v_cvt_f32_ubyte0_e32 v214, v178
	v_cvt_f32_ubyte1_e32 v215, v178
	v_cvt_f32_ubyte2_e32 v218, v178
	v_cvt_f32_ubyte3_e32 v219, v178
	v_rcp_iflag_f32_e32 v214, v214
	v_rcp_iflag_f32_e32 v215, v215
	v_rcp_iflag_f32_e32 v218, v218
	v_rcp_iflag_f32_e32 v219, v219
	v_mul_f32_e32 v210, v214, v210
	v_mul_f32_e32 v211, v215, v211
	v_mul_f32_e32 v212, v218, v212
	v_mul_f32_e32 v213, v219, v213
	v_pk_mul_f32 v[114:115], v[114:115], v[210:211]
	v_pk_mul_f32 v[116:117], v[116:117], v[212:213]
	v_cvt_f32_ubyte0_e32 v210, v175
	v_cvt_f32_ubyte1_e32 v211, v175
	v_cvt_f32_ubyte2_e32 v212, v175
	v_cvt_f32_ubyte3_e32 v213, v175
	v_cvt_f32_ubyte0_e32 v214, v179
	v_cvt_f32_ubyte1_e32 v215, v179
	v_cvt_f32_ubyte2_e32 v218, v179
	v_cvt_f32_ubyte3_e32 v219, v179
	v_rcp_iflag_f32_e32 v214, v214
	v_rcp_iflag_f32_e32 v215, v215
	v_rcp_iflag_f32_e32 v218, v218
	v_rcp_iflag_f32_e32 v219, v219
	v_mul_f32_e32 v210, v214, v210
	v_mul_f32_e32 v211, v215, v211
	v_mul_f32_e32 v212, v218, v212
	v_mul_f32_e32 v213, v219, v213
	v_pk_mul_f32 v[110:111], v[110:111], v[210:211]
	v_pk_mul_f32 v[112:113], v[112:113], v[212:213]
	v_cvt_f32_ubyte0_e32 v210, v176
	v_cvt_f32_ubyte1_e32 v211, v176
	v_cvt_f32_ubyte2_e32 v212, v176
	v_cvt_f32_ubyte3_e32 v213, v176
	v_cvt_f32_ubyte0_e32 v214, v180
	v_cvt_f32_ubyte1_e32 v215, v180
	v_cvt_f32_ubyte2_e32 v218, v180
	v_cvt_f32_ubyte3_e32 v219, v180
	v_rcp_iflag_f32_e32 v214, v214
	v_rcp_iflag_f32_e32 v215, v215
	v_rcp_iflag_f32_e32 v218, v218
	v_rcp_iflag_f32_e32 v219, v219
	v_mul_f32_e32 v210, v214, v210
	v_mul_f32_e32 v211, v215, v211
	v_mul_f32_e32 v212, v218, v212
	v_mul_f32_e32 v213, v219, v213
	v_pk_mul_f32 v[82:83], v[82:83], v[210:211]
	v_pk_mul_f32 v[84:85], v[84:85], v[212:213]
	v_cvt_f32_ubyte0_e32 v210, v177
	v_cvt_f32_ubyte1_e32 v211, v177
	v_cvt_f32_ubyte2_e32 v212, v177
	v_cvt_f32_ubyte3_e32 v213, v177
	v_cvt_f32_ubyte0_e32 v214, v181
	v_cvt_f32_ubyte1_e32 v215, v181
	v_cvt_f32_ubyte2_e32 v218, v181
	v_cvt_f32_ubyte3_e32 v219, v181
	v_rcp_iflag_f32_e32 v214, v214
	v_rcp_iflag_f32_e32 v215, v215
	v_rcp_iflag_f32_e32 v218, v218
	v_rcp_iflag_f32_e32 v219, v219
	v_mul_f32_e32 v210, v214, v210
	v_mul_f32_e32 v211, v215, v211
	v_mul_f32_e32 v212, v218, v212
	v_mul_f32_e32 v213, v219, v213
	v_pk_mul_f32 v[78:79], v[78:79], v[210:211]
	v_pk_mul_f32 v[80:81], v[80:81], v[212:213]
	v_cvt_f32_ubyte0_e32 v210, v166
	v_cvt_f32_ubyte1_e32 v211, v166
	v_cvt_f32_ubyte2_e32 v212, v166
	v_cvt_f32_ubyte3_e32 v213, v166
	v_cvt_f32_ubyte0_e32 v214, v170
	v_cvt_f32_ubyte1_e32 v215, v170
	v_cvt_f32_ubyte2_e32 v218, v170
	v_cvt_f32_ubyte3_e32 v219, v170
	v_rcp_iflag_f32_e32 v214, v214
	v_rcp_iflag_f32_e32 v215, v215
	v_rcp_iflag_f32_e32 v218, v218
	v_rcp_iflag_f32_e32 v219, v219
	v_mul_f32_e32 v210, v214, v210
	v_mul_f32_e32 v211, v215, v211
	v_mul_f32_e32 v212, v218, v212
	v_mul_f32_e32 v213, v219, v213
	v_pk_mul_f32 v[106:107], v[106:107], v[210:211]
	v_pk_mul_f32 v[108:109], v[108:109], v[212:213]
	v_cvt_f32_ubyte0_e32 v210, v167
	v_cvt_f32_ubyte1_e32 v211, v167
	v_cvt_f32_ubyte2_e32 v212, v167
	v_cvt_f32_ubyte3_e32 v213, v167
	v_cvt_f32_ubyte0_e32 v214, v171
	v_cvt_f32_ubyte1_e32 v215, v171
	v_cvt_f32_ubyte2_e32 v218, v171
	v_cvt_f32_ubyte3_e32 v219, v171
	v_rcp_iflag_f32_e32 v214, v214
	v_rcp_iflag_f32_e32 v215, v215
	v_rcp_iflag_f32_e32 v218, v218
	v_rcp_iflag_f32_e32 v219, v219
	v_mul_f32_e32 v210, v214, v210
	v_mul_f32_e32 v211, v215, v211
	v_mul_f32_e32 v212, v218, v212
	v_mul_f32_e32 v213, v219, v213
	v_pk_mul_f32 v[102:103], v[102:103], v[210:211]
	v_pk_mul_f32 v[104:105], v[104:105], v[212:213]
	v_cvt_f32_ubyte0_e32 v210, v168
	v_cvt_f32_ubyte1_e32 v211, v168
	v_cvt_f32_ubyte2_e32 v212, v168
	v_cvt_f32_ubyte3_e32 v213, v168
	v_cvt_f32_ubyte0_e32 v214, v172
	v_cvt_f32_ubyte1_e32 v215, v172
	v_cvt_f32_ubyte2_e32 v218, v172
	v_cvt_f32_ubyte3_e32 v219, v172
	v_rcp_iflag_f32_e32 v214, v214
	v_rcp_iflag_f32_e32 v215, v215
	v_rcp_iflag_f32_e32 v218, v218
	v_rcp_iflag_f32_e32 v219, v219
	v_mul_f32_e32 v210, v214, v210
	v_mul_f32_e32 v211, v215, v211
	v_mul_f32_e32 v212, v218, v212
	v_mul_f32_e32 v213, v219, v213
	v_pk_mul_f32 v[74:75], v[74:75], v[210:211]
	v_pk_mul_f32 v[76:77], v[76:77], v[212:213]
	v_cvt_f32_ubyte0_e32 v210, v169
	v_cvt_f32_ubyte1_e32 v211, v169
	v_cvt_f32_ubyte2_e32 v212, v169
	v_cvt_f32_ubyte3_e32 v213, v169
	v_cvt_f32_ubyte0_e32 v214, v173
	v_cvt_f32_ubyte1_e32 v215, v173
	v_cvt_f32_ubyte2_e32 v218, v173
	v_cvt_f32_ubyte3_e32 v219, v173
	v_rcp_iflag_f32_e32 v214, v214
	v_rcp_iflag_f32_e32 v215, v215
	v_rcp_iflag_f32_e32 v218, v218
	v_rcp_iflag_f32_e32 v219, v219
	v_mul_f32_e32 v210, v214, v210
	v_mul_f32_e32 v211, v215, v211
	v_mul_f32_e32 v212, v218, v212
	v_mul_f32_e32 v213, v219, v213
	v_pk_mul_f32 v[70:71], v[70:71], v[210:211]
	v_pk_mul_f32 v[72:73], v[72:73], v[212:213]
	v_cvt_f32_ubyte0_e32 v210, v158
	v_cvt_f32_ubyte1_e32 v211, v158
	v_cvt_f32_ubyte2_e32 v212, v158
	v_cvt_f32_ubyte3_e32 v213, v158
	v_cvt_f32_ubyte0_e32 v214, v162
	v_cvt_f32_ubyte1_e32 v215, v162
	v_cvt_f32_ubyte2_e32 v218, v162
	v_cvt_f32_ubyte3_e32 v219, v162
	v_rcp_iflag_f32_e32 v214, v214
	v_rcp_iflag_f32_e32 v215, v215
	v_rcp_iflag_f32_e32 v218, v218
	v_rcp_iflag_f32_e32 v219, v219
	v_mul_f32_e32 v210, v214, v210
	v_mul_f32_e32 v211, v215, v211
	v_mul_f32_e32 v212, v218, v212
	v_mul_f32_e32 v213, v219, v213
	v_pk_mul_f32 v[66:67], v[66:67], v[210:211]
	v_pk_mul_f32 v[68:69], v[68:69], v[212:213]
	v_cvt_f32_ubyte0_e32 v210, v159
	v_cvt_f32_ubyte1_e32 v211, v159
	v_cvt_f32_ubyte2_e32 v212, v159
	v_cvt_f32_ubyte3_e32 v213, v159
	v_cvt_f32_ubyte0_e32 v214, v163
	v_cvt_f32_ubyte1_e32 v215, v163
	v_cvt_f32_ubyte2_e32 v218, v163
	v_cvt_f32_ubyte3_e32 v219, v163
	v_rcp_iflag_f32_e32 v214, v214
	v_rcp_iflag_f32_e32 v215, v215
	v_rcp_iflag_f32_e32 v218, v218
	v_rcp_iflag_f32_e32 v219, v219
	v_mul_f32_e32 v210, v214, v210
	v_mul_f32_e32 v211, v215, v211
	v_mul_f32_e32 v212, v218, v212
	v_mul_f32_e32 v213, v219, v213
	v_pk_mul_f32 v[62:63], v[62:63], v[210:211]
	v_pk_mul_f32 v[64:65], v[64:65], v[212:213]
	v_cvt_f32_ubyte0_e32 v210, v160
	v_cvt_f32_ubyte1_e32 v211, v160
	v_cvt_f32_ubyte2_e32 v212, v160
	v_cvt_f32_ubyte3_e32 v213, v160
	v_cvt_f32_ubyte0_e32 v214, v164
	v_cvt_f32_ubyte1_e32 v215, v164
	v_cvt_f32_ubyte2_e32 v218, v164
	v_cvt_f32_ubyte3_e32 v219, v164
	v_rcp_iflag_f32_e32 v214, v214
	v_rcp_iflag_f32_e32 v215, v215
	v_rcp_iflag_f32_e32 v218, v218
	v_rcp_iflag_f32_e32 v219, v219
	v_mul_f32_e32 v210, v214, v210
	v_mul_f32_e32 v211, v215, v211
	v_mul_f32_e32 v212, v218, v212
	v_mul_f32_e32 v213, v219, v213
	v_pk_mul_f32 v[28:29], v[28:29], v[210:211]
	v_pk_mul_f32 v[30:31], v[30:31], v[212:213]
	v_cvt_f32_ubyte0_e32 v210, v161
	v_cvt_f32_ubyte1_e32 v211, v161
	v_cvt_f32_ubyte2_e32 v212, v161
	v_cvt_f32_ubyte3_e32 v213, v161
	v_cvt_f32_ubyte0_e32 v214, v165
	v_cvt_f32_ubyte1_e32 v215, v165
	v_cvt_f32_ubyte2_e32 v218, v165
	v_cvt_f32_ubyte3_e32 v219, v165
	v_rcp_iflag_f32_e32 v214, v214
	v_rcp_iflag_f32_e32 v215, v215
	v_rcp_iflag_f32_e32 v218, v218
	v_rcp_iflag_f32_e32 v219, v219
	v_mul_f32_e32 v210, v214, v210
	v_mul_f32_e32 v211, v215, v211
	v_mul_f32_e32 v212, v218, v212
	v_mul_f32_e32 v213, v219, v213
	v_pk_mul_f32 v[24:25], v[24:25], v[210:211]
	v_pk_mul_f32 v[26:27], v[26:27], v[212:213]
	v_cvt_f32_ubyte0_e32 v210, v150
	v_cvt_f32_ubyte1_e32 v211, v150
	v_cvt_f32_ubyte2_e32 v212, v150
	v_cvt_f32_ubyte3_e32 v213, v150
	v_cvt_f32_ubyte0_e32 v214, v154
	v_cvt_f32_ubyte1_e32 v215, v154
	v_cvt_f32_ubyte2_e32 v218, v154
	v_cvt_f32_ubyte3_e32 v219, v154
	v_rcp_iflag_f32_e32 v214, v214
	v_rcp_iflag_f32_e32 v215, v215
	v_rcp_iflag_f32_e32 v218, v218
	v_rcp_iflag_f32_e32 v219, v219
	v_mul_f32_e32 v210, v214, v210
	v_mul_f32_e32 v211, v215, v211
	v_mul_f32_e32 v212, v218, v212
	v_mul_f32_e32 v213, v219, v213
	v_pk_mul_f32 v[58:59], v[58:59], v[210:211]
	v_pk_mul_f32 v[60:61], v[60:61], v[212:213]
	v_cvt_f32_ubyte0_e32 v210, v151
	v_cvt_f32_ubyte1_e32 v211, v151
	v_cvt_f32_ubyte2_e32 v212, v151
	v_cvt_f32_ubyte3_e32 v213, v151
	v_cvt_f32_ubyte0_e32 v214, v155
	v_cvt_f32_ubyte1_e32 v215, v155
	v_cvt_f32_ubyte2_e32 v218, v155
	v_cvt_f32_ubyte3_e32 v219, v155
	v_rcp_iflag_f32_e32 v214, v214
	v_rcp_iflag_f32_e32 v215, v215
	v_rcp_iflag_f32_e32 v218, v218
	v_rcp_iflag_f32_e32 v219, v219
	v_mul_f32_e32 v210, v214, v210
	v_mul_f32_e32 v211, v215, v211
	v_mul_f32_e32 v212, v218, v212
	v_mul_f32_e32 v213, v219, v213
	v_pk_mul_f32 v[54:55], v[54:55], v[210:211]
	v_pk_mul_f32 v[56:57], v[56:57], v[212:213]
	v_cvt_f32_ubyte0_e32 v210, v152
	v_cvt_f32_ubyte1_e32 v211, v152
	v_cvt_f32_ubyte2_e32 v212, v152
	v_cvt_f32_ubyte3_e32 v213, v152
	v_cvt_f32_ubyte0_e32 v214, v156
	v_cvt_f32_ubyte1_e32 v215, v156
	v_cvt_f32_ubyte2_e32 v218, v156
	v_cvt_f32_ubyte3_e32 v219, v156
	v_rcp_iflag_f32_e32 v214, v214
	v_rcp_iflag_f32_e32 v215, v215
	v_rcp_iflag_f32_e32 v218, v218
	v_rcp_iflag_f32_e32 v219, v219
	v_mul_f32_e32 v210, v214, v210
	v_mul_f32_e32 v211, v215, v211
	v_mul_f32_e32 v212, v218, v212
	v_mul_f32_e32 v213, v219, v213
	v_pk_mul_f32 v[20:21], v[20:21], v[210:211]
	v_pk_mul_f32 v[22:23], v[22:23], v[212:213]
	v_cvt_f32_ubyte0_e32 v210, v153
	v_cvt_f32_ubyte1_e32 v211, v153
	v_cvt_f32_ubyte2_e32 v212, v153
	v_cvt_f32_ubyte3_e32 v213, v153
	v_cvt_f32_ubyte0_e32 v214, v157
	v_cvt_f32_ubyte1_e32 v215, v157
	v_cvt_f32_ubyte2_e32 v218, v157
	v_cvt_f32_ubyte3_e32 v219, v157
	v_rcp_iflag_f32_e32 v214, v214
	v_rcp_iflag_f32_e32 v215, v215
	v_rcp_iflag_f32_e32 v218, v218
	v_rcp_iflag_f32_e32 v219, v219
	v_mul_f32_e32 v210, v214, v210
	v_mul_f32_e32 v211, v215, v211
	v_mul_f32_e32 v212, v218, v212
	v_mul_f32_e32 v213, v219, v213
	v_pk_mul_f32 v[16:17], v[16:17], v[210:211]
	v_pk_mul_f32 v[18:19], v[18:19], v[212:213]
	v_cvt_f32_ubyte0_e32 v210, v142
	v_cvt_f32_ubyte1_e32 v211, v142
	v_cvt_f32_ubyte2_e32 v212, v142
	v_cvt_f32_ubyte3_e32 v213, v142
	v_cvt_f32_ubyte0_e32 v214, v146
	v_cvt_f32_ubyte1_e32 v215, v146
	v_cvt_f32_ubyte2_e32 v218, v146
	v_cvt_f32_ubyte3_e32 v219, v146
	v_rcp_iflag_f32_e32 v214, v214
	v_rcp_iflag_f32_e32 v215, v215
	v_rcp_iflag_f32_e32 v218, v218
	v_rcp_iflag_f32_e32 v219, v219
	v_mul_f32_e32 v210, v214, v210
	v_mul_f32_e32 v211, v215, v211
	v_mul_f32_e32 v212, v218, v212
	v_mul_f32_e32 v213, v219, v213
	v_pk_mul_f32 v[50:51], v[50:51], v[210:211]
	v_pk_mul_f32 v[52:53], v[52:53], v[212:213]
	v_cvt_f32_ubyte0_e32 v210, v143
	v_cvt_f32_ubyte1_e32 v211, v143
	v_cvt_f32_ubyte2_e32 v212, v143
	v_cvt_f32_ubyte3_e32 v213, v143
	v_cvt_f32_ubyte0_e32 v214, v147
	v_cvt_f32_ubyte1_e32 v215, v147
	v_cvt_f32_ubyte2_e32 v218, v147
	v_cvt_f32_ubyte3_e32 v219, v147
	v_rcp_iflag_f32_e32 v214, v214
	v_rcp_iflag_f32_e32 v215, v215
	v_rcp_iflag_f32_e32 v218, v218
	v_rcp_iflag_f32_e32 v219, v219
	v_mul_f32_e32 v210, v214, v210
	v_mul_f32_e32 v211, v215, v211
	v_mul_f32_e32 v212, v218, v212
	v_mul_f32_e32 v213, v219, v213
	v_pk_mul_f32 v[46:47], v[46:47], v[210:211]
	v_pk_mul_f32 v[48:49], v[48:49], v[212:213]
	v_cvt_f32_ubyte0_e32 v210, v144
	v_cvt_f32_ubyte1_e32 v211, v144
	v_cvt_f32_ubyte2_e32 v212, v144
	v_cvt_f32_ubyte3_e32 v213, v144
	v_cvt_f32_ubyte0_e32 v214, v148
	v_cvt_f32_ubyte1_e32 v215, v148
	v_cvt_f32_ubyte2_e32 v218, v148
	v_cvt_f32_ubyte3_e32 v219, v148
	v_rcp_iflag_f32_e32 v214, v214
	v_rcp_iflag_f32_e32 v215, v215
	v_rcp_iflag_f32_e32 v218, v218
	v_rcp_iflag_f32_e32 v219, v219
	v_mul_f32_e32 v210, v214, v210
	v_mul_f32_e32 v211, v215, v211
	v_mul_f32_e32 v212, v218, v212
	v_mul_f32_e32 v213, v219, v213
	v_pk_mul_f32 v[12:13], v[12:13], v[210:211]
	v_pk_mul_f32 v[14:15], v[14:15], v[212:213]
	v_cvt_f32_ubyte0_e32 v210, v145
	v_cvt_f32_ubyte1_e32 v211, v145
	v_cvt_f32_ubyte2_e32 v212, v145
	v_cvt_f32_ubyte3_e32 v213, v145
	v_cvt_f32_ubyte0_e32 v214, v149
	v_cvt_f32_ubyte1_e32 v215, v149
	v_cvt_f32_ubyte2_e32 v218, v149
	v_cvt_f32_ubyte3_e32 v219, v149
	v_rcp_iflag_f32_e32 v214, v214
	v_rcp_iflag_f32_e32 v215, v215
	v_rcp_iflag_f32_e32 v218, v218
	v_rcp_iflag_f32_e32 v219, v219
	v_mul_f32_e32 v210, v214, v210
	v_mul_f32_e32 v211, v215, v211
	v_mul_f32_e32 v212, v218, v212
	v_mul_f32_e32 v213, v219, v213
	v_pk_mul_f32 v[8:9], v[8:9], v[210:211]
	v_pk_mul_f32 v[10:11], v[10:11], v[212:213]
	v_cvt_f32_ubyte0_e32 v210, v134
	v_cvt_f32_ubyte1_e32 v211, v134
	v_cvt_f32_ubyte2_e32 v212, v134
	v_cvt_f32_ubyte3_e32 v213, v134
	v_cvt_f32_ubyte0_e32 v214, v138
	v_cvt_f32_ubyte1_e32 v215, v138
	v_cvt_f32_ubyte2_e32 v218, v138
	v_cvt_f32_ubyte3_e32 v219, v138
	v_rcp_iflag_f32_e32 v214, v214
	v_rcp_iflag_f32_e32 v215, v215
	v_rcp_iflag_f32_e32 v218, v218
	v_rcp_iflag_f32_e32 v219, v219
	v_mul_f32_e32 v210, v214, v210
	v_mul_f32_e32 v211, v215, v211
	v_mul_f32_e32 v212, v218, v212
	v_mul_f32_e32 v213, v219, v213
	v_pk_mul_f32 v[42:43], v[42:43], v[210:211]
	v_pk_mul_f32 v[44:45], v[44:45], v[212:213]
	v_cvt_f32_ubyte0_e32 v210, v135
	v_cvt_f32_ubyte1_e32 v211, v135
	v_cvt_f32_ubyte2_e32 v212, v135
	v_cvt_f32_ubyte3_e32 v213, v135
	v_cvt_f32_ubyte0_e32 v214, v139
	v_cvt_f32_ubyte1_e32 v215, v139
	v_cvt_f32_ubyte2_e32 v218, v139
	v_cvt_f32_ubyte3_e32 v219, v139
	v_rcp_iflag_f32_e32 v214, v214
	v_rcp_iflag_f32_e32 v215, v215
	v_rcp_iflag_f32_e32 v218, v218
	v_rcp_iflag_f32_e32 v219, v219
	v_mul_f32_e32 v210, v214, v210
	v_mul_f32_e32 v211, v215, v211
	v_mul_f32_e32 v212, v218, v212
	v_mul_f32_e32 v213, v219, v213
	v_pk_mul_f32 v[38:39], v[38:39], v[210:211]
	v_pk_mul_f32 v[40:41], v[40:41], v[212:213]
	v_cvt_f32_ubyte0_e32 v210, v136
	v_cvt_f32_ubyte1_e32 v211, v136
	v_cvt_f32_ubyte2_e32 v212, v136
	v_cvt_f32_ubyte3_e32 v213, v136
	v_cvt_f32_ubyte0_e32 v214, v140
	v_cvt_f32_ubyte1_e32 v215, v140
	v_cvt_f32_ubyte2_e32 v218, v140
	v_cvt_f32_ubyte3_e32 v219, v140
	v_rcp_iflag_f32_e32 v214, v214
	v_rcp_iflag_f32_e32 v215, v215
	v_rcp_iflag_f32_e32 v218, v218
	v_rcp_iflag_f32_e32 v219, v219
	v_mul_f32_e32 v210, v214, v210
	v_mul_f32_e32 v211, v215, v211
	v_mul_f32_e32 v212, v218, v212
	v_mul_f32_e32 v213, v219, v213
	v_pk_mul_f32 v[4:5], v[4:5], v[210:211]
	v_pk_mul_f32 v[6:7], v[6:7], v[212:213]
	v_cvt_f32_ubyte0_e32 v210, v137
	v_cvt_f32_ubyte1_e32 v211, v137
	v_cvt_f32_ubyte2_e32 v212, v137
	v_cvt_f32_ubyte3_e32 v213, v137
	v_cvt_f32_ubyte0_e32 v214, v141
	v_cvt_f32_ubyte1_e32 v215, v141
	v_cvt_f32_ubyte2_e32 v218, v141
	v_cvt_f32_ubyte3_e32 v219, v141
	v_rcp_iflag_f32_e32 v214, v214
	v_rcp_iflag_f32_e32 v215, v215
	v_rcp_iflag_f32_e32 v218, v218
	v_rcp_iflag_f32_e32 v219, v219
	v_mul_f32_e32 v210, v214, v210
	v_mul_f32_e32 v211, v215, v211
	v_mul_f32_e32 v212, v218, v212
	v_mul_f32_e32 v213, v219, v213
	v_pk_mul_f32 v[0:1], v[0:1], v[210:211]
	v_pk_mul_f32 v[2:3], v[2:3], v[212:213]
	s_branch .LBB0_1465
